# counted vmcnt waits: second-half K/V staging writes in the GQA and NA loops no longer drain the next tile loads (strategy 1: waitcnt placement) on top of staggered GEMM starts
# baseline (speedup 1.0000x reference)
; #define SBAR() __builtin_amdgcn_sched_barrier(0)
; #define SLOAD(i, k0) do { sr_[i].vs0 = ld8(&Vh[(long)((k0) + sr) * LDK + sc]); sr_[i].vs1 = ld8(&Vh[(long)((k0) + 32 + sr) * LDK + sc]); \
;     sr_[i].ks0 = ld8(&Kh[(long)((k0) + sr) * LDK + sc]); sr_[i].ks1 = ld8(&Kh[(long)((k0) + 32 + sr) * LDK + sc]); } while (0)
; #define SWRITE(b, i) do { *(bf16x8*)((char*)V_lds + (b) * SHM_V + vst0) = sr_[i].vs0;          \
;     *(bf16x8*)((char*)V_lds + (b) * SHM_V + vst1) = sr_[i].vs1; int kc = sc * 2;               \
;     *(bf16x8*)((char*)K_lds + (b) * SHM_K + KSWZ(sr, kc)) = sr_[i].ks0;                       \
;     *(bf16x8*)((char*)K_lds + (b) * SHM_K + KSWZ(32 + sr, kc)) = sr_[i].ks1; } while (0)
; #define SWAIT() asm volatile("s_waitcnt vmcnt(4)" ::: "memory")
; #define RESC(a) do { if (__any((a) < 1.f)) { if (hi == 0) al_l[r32] = (a); asm volatile("s_waitcnt lgkmcnt(0)" ::: "memory"); \
;     _Pragma("unroll") for (int d = 0; d < 4; ++d) _Pragma("unroll") for (int r = 0; r < 16; ++r) o[d][r] *= al_l[crow(r, hi)]; } } while (0)
; #define F8_MFMA(A, B, C) __builtin_amdgcn_mfma_scale_f32_32x32x64_f8f6f4(A, B, C, 0, 0, 0, 0x7f7f7f7f, 0, 0x7f7f7f7f)
; #define F8_CAT(lo, hi) __builtin_shufflevector(lo, hi, 0, 1, 2, 3, 4, 5, 6, 7)
; #define SWAIT() asm volatile("s_waitcnt vmcnt(2)" ::: "memory")
; __device__ __forceinline__ void pv8(f32x16* o, const char* Vs, i32x8 pa, int r32, int hi) {
; #pragma unroll
;   for (int db = 0; db < 4; ++db) { const int d = 32 * db + r32, f = (d >> 2) & 3; const char* vr = Vs + d * 64;
;     const i32x8 b = F8_CAT(*(const i32x4*)(vr + (((2 * hi) ^ f) << 4)), *(const i32x4*)(vr + (((2 * hi + 1) ^ f) << 4)));
;     o[db] = F8_MFMA(pa, b, o[db]); }
; }
; template <int LDQ, int LDK, int LDO, int OSH>
; __device__ __forceinline__ void attn_body_f8(const unsigned char* Qb, const unsigned char* __restrict__ Kh, const unsigned char* __restrict__ VTh, long ldv, unsigned char* Ob, int seq, char* lds) {
;     ...
;     __syncthreads(); SWAIT(); SWRITE(0, SE);
;     RESC(alB); __syncthreads();
;     SBAR(); qkt8(pA0, pA1, K_lds, q8, r32, hi);
;     finishSM8(pB0, pB1, alB, l_reg, pa); SBAR();
;     if (j + 3 < NT) SLOAD(SE, (j + 3) * KVBLK); SBAR();
;     PV8(1, pa); partialSM8<5>(pA0, pA1, m_reg, mnA, alA);
;     __syncthreads(); SWAIT(); SWRITE(1, SO);
;     RESC(alA); __syncthreads();
.LBB0_377:
	s_waitcnt lgkmcnt(0)
	s_barrier
	v_mfma_scale_f32_32x32x64_f8f6f4 v[2:17], v[238:245], v[146:153], v[2:17], v216, v216 op_sel_hi:[0,0,0]
	s_waitcnt vmcnt(2)
	v_cmp_gt_f32_e32 vcc, 1.0, v188
	s_cmp_eq_u64 s[8:9], 0
	s_cbranch_scc1 .Lgqa_ld_inflight
	s_waitcnt vmcnt(0)
.Lgqa_ld_inflight:
	ds_write_b128 v225, v[162:165] offset:8192
	ds_write_b128 v226, v[166:169] offset:24576
	v_sub_f32_e32 v66, v101, v236
	v_sub_f32_e32 v67, v100, v236
	v_sub_f32_e32 v68, v99, v236
	v_sub_f32_e32 v69, v98, v236
	v_sub_f32_e32 v97, v97, v236
	v_sub_f32_e32 v96, v96, v236
	v_sub_f32_e32 v95, v95, v236
	v_sub_f32_e32 v94, v94, v236
	v_mfma_scale_f32_32x32x64_f8f6f4 v[50:65], v[238:245], v[138:145], v[50:65], v216, v216 op_sel_hi:[0,0,0]
	v_sub_f32_e32 v93, v93, v236
	v_sub_f32_e32 v92, v92, v236
	v_sub_f32_e32 v91, v91, v236
	v_sub_f32_e32 v90, v90, v236
	v_sub_f32_e32 v89, v89, v236
	v_sub_f32_e32 v88, v88, v236
	v_sub_f32_e32 v87, v87, v236
	v_sub_f32_e32 v86, v86, v236
	v_exp_f32_e32 v186, v86
	v_exp_f32_e32 v187, v87
	v_exp_f32_e32 v148, v88
	v_exp_f32_e32 v149, v89
	v_exp_f32_e32 v182, v90
	v_exp_f32_e32 v183, v91
	v_exp_f32_e32 v152, v92
	v_exp_f32_e32 v153, v93
	v_mfma_scale_f32_32x32x64_f8f6f4 v[34:49], v[238:245], v[130:137], v[34:49], v216, v216 op_sel_hi:[0,0,0]
	v_exp_f32_e32 v184, v94
	v_exp_f32_e32 v185, v95
	v_exp_f32_e32 v146, v96
	v_exp_f32_e32 v147, v97
	v_exp_f32_e32 v180, v69
	v_exp_f32_e32 v181, v68
	v_exp_f32_e32 v150, v67
	v_exp_f32_e32 v151, v66
	v_sub_f32_e32 v68, v82, v236
	v_add_f32_e32 v82, v178, v235
	v_fmac_f32_e32 v82, v234, v0
	v_add_f32_e32 v0, v110, v111
	s_mov_b64 s[10:11], 0x8000
	v_sub_f32_e32 v67, v85, v236
	v_sub_f32_e32 v66, v84, v236
	v_sub_f32_e32 v69, v83, v236
	v_sub_f32_e32 v81, v81, v236
	v_sub_f32_e32 v80, v80, v236
	v_sub_f32_e32 v79, v79, v236
	v_sub_f32_e32 v78, v78, v236
	v_mfma_scale_f32_32x32x64_f8f6f4 v[18:33], v[238:245], v[102:109], v[18:33], v216, v216 op_sel_hi:[0,0,0]
	v_sub_f32_e32 v77, v77, v236
	v_sub_f32_e32 v76, v76, v236
	v_sub_f32_e32 v75, v75, v236
	v_sub_f32_e32 v74, v74, v236
	v_sub_f32_e32 v73, v73, v236
	v_sub_f32_e32 v72, v72, v236
	v_fmac_f32_e32 v0, v82, v237
	v_sub_f32_e32 v71, v71, v236
	v_sub_f32_e32 v70, v70, v236
	v_lshl_add_u64 v[174:175], v[174:175], 0, s[0:1]
	v_lshl_add_u64 v[176:177], v[176:177], 0, s[10:11]
	s_add_i32 s35, s35, 2
	s_cbranch_vccz .LBB0_381
	s_nop 15
	s_and_saveexec_b64 s[10:11], s[2:3]
	ds_write_b32 v229, v188 offset:32896
	s_or_b64 exec, exec, s[10:11]
	s_waitcnt lgkmcnt(0)
	v_add_u32_e32 v112, v173, v228
	ds_read_b128 v[138:141], v112 offset:32992
	ds_read_b128 v[102:105], v112 offset:32960
	ds_read_b128 v[106:109], v112 offset:32928
	ds_read_b128 v[130:133], v112 offset:32896
	s_waitcnt lgkmcnt(3)
	s_nop 1
	v_pk_mul_f32 v[14:15], v[14:15], v[138:139]
	s_waitcnt lgkmcnt(2)
	v_pk_mul_f32 v[10:11], v[10:11], v[102:103]
	s_waitcnt lgkmcnt(1)
	v_pk_mul_f32 v[6:7], v[6:7], v[106:107]
	v_pk_mul_f32 v[16:17], v[16:17], v[140:141]
	v_pk_mul_f32 v[12:13], v[12:13], v[104:105]
	v_pk_mul_f32 v[8:9], v[8:9], v[108:109]
	s_waitcnt lgkmcnt(0)
	v_pk_mul_f32 v[4:5], v[4:5], v[132:133]
	v_pk_mul_f32 v[2:3], v[2:3], v[130:131]
	v_pk_mul_f32 v[62:63], v[62:63], v[138:139]
	v_pk_mul_f32 v[58:59], v[58:59], v[102:103]
	v_pk_mul_f32 v[54:55], v[54:55], v[106:107]
	v_pk_mul_f32 v[64:65], v[64:65], v[140:141]
	v_pk_mul_f32 v[60:61], v[60:61], v[104:105]
	v_pk_mul_f32 v[56:57], v[56:57], v[108:109]
	v_pk_mul_f32 v[52:53], v[52:53], v[132:133]
	v_pk_mul_f32 v[50:51], v[50:51], v[130:131]
	v_pk_mul_f32 v[46:47], v[46:47], v[138:139]
	v_pk_mul_f32 v[42:43], v[42:43], v[102:103]
	v_pk_mul_f32 v[38:39], v[38:39], v[106:107]
	v_pk_mul_f32 v[48:49], v[48:49], v[140:141]
	v_pk_mul_f32 v[44:45], v[44:45], v[104:105]
	v_pk_mul_f32 v[40:41], v[40:41], v[108:109]
	v_pk_mul_f32 v[36:37], v[36:37], v[132:133]
	v_pk_mul_f32 v[34:35], v[34:35], v[130:131]
	v_pk_mul_f32 v[30:31], v[30:31], v[138:139]
	v_pk_mul_f32 v[26:27], v[26:27], v[102:103]
	v_pk_mul_f32 v[22:23], v[22:23], v[106:107]
	v_pk_mul_f32 v[32:33], v[32:33], v[140:141]
	v_pk_mul_f32 v[28:29], v[28:29], v[104:105]
	v_pk_mul_f32 v[24:25], v[24:25], v[108:109]
	v_pk_mul_f32 v[20:21], v[20:21], v[132:133]
	v_pk_mul_f32 v[18:19], v[18:19], v[130:131]

; #define LAS __attribute__((address_space(3)))
;   constexpr float C = SCALE * 1.4426950408889634f; constexpr float THR = (float)THRV;
;   float pmax = p0[0];
; #pragma unroll
;   for (int r = 1; r < 16; ++r) pmax = fmaxf(pmax, p0[r]);
; #pragma unroll
;   for (int r = 0; r < 16; ++r) pmax = fmaxf(pmax, p1[r]);
;   { auto rr = __builtin_amdgcn_permlane32_swap(__float_as_uint(pmax), __float_as_uint(pmax), false, false);
;     pmax = fmaxf(__uint_as_float(rr[0]), __uint_as_float(rr[1])); }
;   if (__builtin_expect(__all(pmax - m_reg <= THR / SCALE), 1)) { mn = m_reg; alpha = 1.f; }
;   else { mn = fmaxf(m_reg, pmax); alpha = __builtin_amdgcn_exp2f((m_reg - mn) * C); m_reg = mn; }
; __device__ __forceinline__ void na_mask(f32x16& p0, f32x16& p1, const NaCtx& n, int tile, int hi) {
;   const int kr = n.kr0 + tile; const bool vrow = (kr >= n.rs) && (kr < n.rs + 8);
;   int dr = kr - n.r + 7; dr = dr < 0 ? 0 : (dr > 14 ? 14 : dr);
;   const LAS float* t = n.tbl + dr * 32 + 15 - n.c;
;   const float NEG = -INFINITY;
;   const int d0 = 4 * hi - n.cs;
; #pragma unroll
;   for (int rr = 0; rr < 16; ++rr) { const int kq = (rr & 3) + 8 * (rr >> 2);
;     const bool ok0 = vrow && ((unsigned)(kq + d0) < 16u), ok1 = vrow && ((unsigned)(kq + 32 + d0) < 16u);
;     const float b0 = t[kq + 4 * hi], b1 = t[kq + 4 * hi + 32];
;     p0[rr] = ok0 ? p0[rr] + b0 : NEG; p1[rr] = ok1 ? p1[rr] + b1 : NEG;
;     if ((rr & 3) == 3) asm volatile("" ::: "memory"); }
.LBB0_507:
	s_or_b64 exec, exec, s[26:27]
	s_waitcnt lgkmcnt(1)
	v_add_f32_e32 v80, v80, v181
	s_and_b64 vcc, s[12:13], s[76:77]
	v_cndmask_b32_e32 v80, v221, v80, vcc
	v_add_f32_e32 v79, v79, v180
	s_and_b64 vcc, s[12:13], s[78:79]
	v_cndmask_b32_e32 v79, v221, v79, vcc
	v_add_f32_e32 v78, v78, v179
	s_and_b64 vcc, s[12:13], s[80:81]
	v_cndmask_b32_e32 v78, v221, v78, vcc
	v_add_f32_e32 v77, v77, v178
	s_and_b64 vcc, s[12:13], s[82:83]
	v_cndmask_b32_e32 v77, v221, v77, vcc
	v_add_f32_e32 v76, v76, v177
	s_and_b64 vcc, s[12:13], s[84:85]
	v_cndmask_b32_e32 v76, v221, v76, vcc
	v_add_f32_e32 v75, v75, v176
	s_and_b64 vcc, s[12:13], s[86:87]
	v_cndmask_b32_e32 v75, v221, v75, vcc
	v_add_f32_e32 v74, v74, v175
	s_and_b64 vcc, s[12:13], s[88:89]
	v_cndmask_b32_e32 v74, v221, v74, vcc
	v_add_f32_e32 v73, v73, v174
	s_and_b64 vcc, s[12:13], s[90:91]
	v_cndmask_b32_e32 v73, v221, v73, vcc
	v_add_f32_e32 v72, v72, v113
	s_and_b64 vcc, s[12:13], s[92:93]
	v_cndmask_b32_e32 v72, v221, v72, vcc
	v_add_f32_e32 v71, v71, v112
	s_and_b64 vcc, s[12:13], s[94:95]
	v_cndmask_b32_e32 v71, v221, v71, vcc
	v_add_f32_e32 v70, v70, v105
	s_and_b64 vcc, s[12:13], s[96:97]
	v_cndmask_b32_e32 v70, v221, v70, vcc
	v_add_f32_e32 v69, v69, v103
	s_and_b64 vcc, s[12:13], s[2:3]
	v_cndmask_b32_e32 v69, v221, v69, vcc
	v_add_f32_e32 v68, v68, v102
	s_and_b64 vcc, s[12:13], s[4:5]
	v_cndmask_b32_e32 v68, v221, v68, vcc
	v_add_f32_e32 v67, v67, v101
	s_and_b64 vcc, s[12:13], s[6:7]
	v_cndmask_b32_e32 v67, v221, v67, vcc
	v_add_f32_e32 v66, v66, v100
	s_and_b64 vcc, s[12:13], s[8:9]
	v_cndmask_b32_e32 v66, v221, v66, vcc
	s_waitcnt lgkmcnt(0)
	v_add_f32_e32 v81, v81, v96
	s_and_b64 vcc, s[12:13], s[10:11]
	v_cndmask_b32_e32 v81, v221, v81, vcc
	v_max_f32_e32 v96, v98, v98
	v_max_f32_e32 v97, v99, v99
	v_max_f32_e32 v96, v97, v96
	v_max3_f32 v96, v96, v83, v82
	v_max3_f32 v96, v96, v85, v84
	v_max3_f32 v96, v96, v87, v86
	v_max3_f32 v96, v96, v89, v88
	v_max3_f32 v96, v96, v91, v90
	v_max3_f32 v96, v96, v93, v92
	v_max3_f32 v96, v96, v95, v94
	v_max3_f32 v96, v96, v66, v67
	v_max3_f32 v96, v96, v68, v69
	v_max3_f32 v96, v96, v70, v71
	v_max3_f32 v96, v96, v72, v73
	v_max3_f32 v96, v96, v74, v75
	v_max3_f32 v96, v96, v76, v77
	v_max3_f32 v96, v96, v78, v79
	v_max3_f32 v96, v96, v80, v81
	v_mov_b32_e32 v97, v96
	s_nop 1
	v_permlane32_swap_b32_e32 v96, v97
	v_max_f32_e32 v97, v97, v97
	v_max_f32_e32 v96, v96, v96
	v_max_f32_e32 v96, v96, v97
	v_sub_f32_e32 v97, v96, v107
	v_cmp_ge_f32_e32 vcc, s41, v97
	v_max_f32_e32 v97, v107, v107
	v_max_f32_e32 v96, v97, v96
	v_sub_f32_e32 v97, v107, v96
	v_mul_f32_e32 v97, 0x3e0293ee, v97
	v_exp_f32_e32 v97, v97
	s_cmp_eq_u64 vcc, exec
	s_cselect_b64 s[12:13], -1, 0
	s_barrier
	s_waitcnt vmcnt(4)
	v_cndmask_b32_e64 v179, v97, 1.0, s[12:13]
	v_cmp_gt_f32_e32 vcc, 1.0, v179
	s_cmp_eq_u64 s[24:25], 0
	s_cbranch_scc1 .Lna_ld_inflight
	s_waitcnt vmcnt(0)
.Lna_ld_inflight:
	ds_write_b128 v200, v[108:111] offset:16384
	ds_write_b128 v201, v[162:165] offset:16384
	ds_write_b128 v198, v[166:169] offset:49152
	ds_write_b128 v199, v[170:173] offset:49152
	s_cbranch_vccz .LBB0_511
	s_and_saveexec_b64 s[26:27], s[42:43]
	ds_write_b32 v189, v179 offset:128
	s_or_b64 exec, exec, s[26:27]
	s_waitcnt lgkmcnt(0)
	ds_read_b128 v[100:103], v187 offset:224
	ds_read_b128 v[108:111], v187 offset:192
	ds_read_b128 v[162:165], v187 offset:160
	ds_read_b128 v[166:169], v187 offset:128
	s_waitcnt lgkmcnt(3)
	v_pk_mul_f32 v[64:65], v[64:65], v[102:103]
	s_waitcnt lgkmcnt(2)
	v_pk_mul_f32 v[60:61], v[60:61], v[110:111]
	s_waitcnt lgkmcnt(1)
	v_pk_mul_f32 v[56:57], v[56:57], v[164:165]
	s_waitcnt lgkmcnt(0)
	v_pk_mul_f32 v[52:53], v[52:53], v[168:169]
	v_pk_mul_f32 v[62:63], v[62:63], v[100:101]
	v_pk_mul_f32 v[58:59], v[58:59], v[108:109]
	v_pk_mul_f32 v[54:55], v[54:55], v[162:163]
	v_pk_mul_f32 v[50:51], v[50:51], v[166:167]
	v_pk_mul_f32 v[48:49], v[48:49], v[102:103]
	v_pk_mul_f32 v[44:45], v[44:45], v[110:111]
	v_pk_mul_f32 v[40:41], v[40:41], v[164:165]
	v_pk_mul_f32 v[36:37], v[36:37], v[168:169]
	v_pk_mul_f32 v[46:47], v[46:47], v[100:101]
	v_pk_mul_f32 v[42:43], v[42:43], v[108:109]
	v_pk_mul_f32 v[38:39], v[38:39], v[162:163]
	v_pk_mul_f32 v[34:35], v[34:35], v[166:167]
	v_pk_mul_f32 v[32:33], v[32:33], v[102:103]
	v_pk_mul_f32 v[28:29], v[28:29], v[110:111]
	v_pk_mul_f32 v[24:25], v[24:25], v[164:165]
	v_pk_mul_f32 v[20:21], v[20:21], v[168:169]
	v_pk_mul_f32 v[30:31], v[30:31], v[100:101]
	v_pk_mul_f32 v[26:27], v[26:27], v[108:109]
	v_pk_mul_f32 v[22:23], v[22:23], v[162:163]
	v_pk_mul_f32 v[18:19], v[18:19], v[166:167]
	v_pk_mul_f32 v[16:17], v[16:17], v[102:103]
	v_pk_mul_f32 v[12:13], v[12:13], v[110:111]
	v_pk_mul_f32 v[8:9], v[8:9], v[164:165]
	v_pk_mul_f32 v[4:5], v[4:5], v[168:169]
	v_pk_mul_f32 v[14:15], v[14:15], v[100:101]
	v_pk_mul_f32 v[10:11], v[10:11], v[108:109]
	v_pk_mul_f32 v[6:7], v[6:7], v[162:163]
	v_pk_mul_f32 v[2:3], v[2:3], v[166:167]
